# C39: C38 with the 16 duplicate s_waitcnt lgkmcnt(0) after the barrier at the head of the first MFMA cluster of each GEMM K-loop phase removed (redundant wait removal)
# baseline (speedup 1.0000x reference)
.LBB0_106:
	s_add_u32 s20, s18, 0x100
	s_addc_u32 s21, s19, 0
	s_add_i32 s47, 0, 0x10000
	s_cmp_eq_u32 s46, 12
	s_cselect_b32 s25, s15, s21
	s_cselect_b32 s24, s14, s20
	v_add_u32_e32 v0, s47, v242
	s_cselect_b32 s23, s43, s45
	s_cselect_b32 s22, s42, s44
	s_add_i32 s48, 0, 0x14000
	ds_read_b128 v[98:101], v0
	ds_read_b128 v[110:113], v0 offset:1024
	ds_read_b128 v[122:125], v0 offset:2048
	ds_read_b128 v[130:133], v0 offset:3072
	v_add_u32_e32 v0, s48, v242
	ds_read_b128 v[138:141], v0
	ds_read_b128 v[142:145], v0 offset:1024
	ds_read_b128 v[146:149], v0 offset:2048
	ds_read_b128 v[150:153], v0 offset:3072
	v_lshl_add_u64 v[208:209], s[18:19], 0, v[204:205]
	s_add_i32 m0, s27, 0xc000
	ds_read_b128 v[158:161], v247
	ds_read_b128 v[166:169], v247 offset:1024
	ds_read_b128 v[170:173], v247 offset:2048
	ds_read_b128 v[174:177], v247 offset:3072
	ds_read_b128 v[178:181], v247 offset:4096
	ds_read_b128 v[182:185], v247 offset:5120
	ds_read_b128 v[186:189], v247 offset:6144
	ds_read_b128 v[190:193], v247 offset:7168
	global_load_lds_dwordx4 v[208:209], off
	v_lshl_add_u64 v[208:209], s[18:19], 0, v[206:207]
	s_add_i32 m0, s27, 0xe000
	s_nop 0
	global_load_lds_dwordx4 v[208:209], off
	s_waitcnt vmcnt(8)
	s_waitcnt lgkmcnt(0)
	s_barrier
	s_setprio 1
	v_mfma_f32_16x16x32_bf16 v[162:165], v[98:101], v[158:161], v[162:165]
	v_mfma_f32_16x16x32_bf16 v[154:157], v[122:125], v[158:161], v[154:157]
	v_mfma_f32_16x16x32_bf16 v[118:121], v[98:101], v[170:173], v[118:121]
	v_mfma_f32_16x16x32_bf16 v[114:117], v[122:125], v[170:173], v[114:117]
	v_mfma_f32_16x16x32_bf16 v[94:97], v[98:101], v[178:181], v[94:97]
	v_mfma_f32_16x16x32_bf16 v[90:93], v[122:125], v[178:181], v[90:93]
	v_mfma_f32_16x16x32_bf16 v[78:81], v[98:101], v[186:189], v[78:81]
	v_mfma_f32_16x16x32_bf16 v[74:77], v[122:125], v[186:189], v[74:77]
	v_mfma_f32_16x16x32_bf16 v[162:165], v[110:113], v[166:169], v[162:165]
	v_mfma_f32_16x16x32_bf16 v[154:157], v[130:133], v[166:169], v[154:157]
	v_mfma_f32_16x16x32_bf16 v[118:121], v[110:113], v[174:177], v[118:121]
	v_mfma_f32_16x16x32_bf16 v[114:117], v[130:133], v[174:177], v[114:117]
	v_mfma_f32_16x16x32_bf16 v[94:97], v[110:113], v[182:185], v[94:97]
	v_mfma_f32_16x16x32_bf16 v[90:93], v[130:133], v[182:185], v[90:93]
	v_mfma_f32_16x16x32_bf16 v[78:81], v[110:113], v[190:193], v[78:81]
	v_mfma_f32_16x16x32_bf16 v[74:77], v[130:133], v[190:193], v[74:77]
	v_mfma_f32_16x16x32_bf16 v[134:137], v[138:141], v[158:161], v[134:137]
	v_mfma_f32_16x16x32_bf16 v[126:129], v[146:149], v[158:161], v[126:129]
	v_mfma_f32_16x16x32_bf16 v[106:109], v[138:141], v[170:173], v[106:109]
	v_mfma_f32_16x16x32_bf16 v[102:105], v[146:149], v[170:173], v[102:105]
	v_mfma_f32_16x16x32_bf16 v[86:89], v[138:141], v[178:181], v[86:89]
	v_mfma_f32_16x16x32_bf16 v[82:85], v[146:149], v[178:181], v[82:85]
	v_mfma_f32_16x16x32_bf16 v[70:73], v[138:141], v[186:189], v[70:73]
	v_mfma_f32_16x16x32_bf16 v[66:69], v[146:149], v[186:189], v[66:69]
	v_mfma_f32_16x16x32_bf16 v[134:137], v[142:145], v[166:169], v[134:137]
	v_mfma_f32_16x16x32_bf16 v[126:129], v[150:153], v[166:169], v[126:129]
	v_mfma_f32_16x16x32_bf16 v[106:109], v[142:145], v[174:177], v[106:109]
	v_mfma_f32_16x16x32_bf16 v[102:105], v[150:153], v[174:177], v[102:105]
	v_mfma_f32_16x16x32_bf16 v[86:89], v[142:145], v[182:185], v[86:89]
	v_mfma_f32_16x16x32_bf16 v[82:85], v[150:153], v[182:185], v[82:85]
	v_mfma_f32_16x16x32_bf16 v[70:73], v[142:145], v[190:193], v[70:73]
	v_mfma_f32_16x16x32_bf16 v[66:69], v[150:153], v[190:193], v[66:69]
	s_setprio 0
	s_barrier
	s_add_i32 s18, s47, s26
	v_lshl_add_u64 v[208:209], s[22:23], 0, v[198:199]
	s_mov_b32 m0, s18
	ds_read_b128 v[158:161], v247 offset:16384
	ds_read_b128 v[166:169], v247 offset:17408
	ds_read_b128 v[170:173], v247 offset:18432
	ds_read_b128 v[174:177], v247 offset:19456
	ds_read_b128 v[178:181], v247 offset:20480
	ds_read_b128 v[182:185], v247 offset:21504
	ds_read_b128 v[186:189], v247 offset:22528
	ds_read_b128 v[190:193], v247 offset:23552
	global_load_lds_dwordx4 v[208:209], off
	s_add_i32 m0, s18, 0x2000
	s_add_u32 s18, s22, 0x40000
	v_lshl_add_u64 v[210:211], s[22:23], 0, v[196:197]
	s_addc_u32 s19, s23, 0
	s_add_i32 s47, s48, s26
	global_load_lds_dwordx4 v[210:211], off
	v_lshl_add_u64 v[212:213], s[18:19], 0, v[198:199]
	s_mov_b32 m0, s47
	v_lshl_add_u64 v[214:215], s[24:25], 0, v[196:197]
	global_load_lds_dwordx4 v[212:213], off
	v_lshl_add_u64 v[212:213], s[18:19], 0, v[196:197]
	s_add_i32 m0, s47, 0x2000
	s_nop 0
	global_load_lds_dwordx4 v[212:213], off
	v_lshl_add_u64 v[212:213], s[24:25], 0, v[198:199]
	s_mov_b32 m0, s27
	s_nop 0
	global_load_lds_dwordx4 v[212:213], off
	s_mov_b32 m0, s28
	s_nop 0
	global_load_lds_dwordx4 v[214:215], off
	s_waitcnt vmcnt(8)
	s_waitcnt lgkmcnt(0)
	s_barrier
	s_setprio 1
	v_mfma_f32_16x16x32_bf16 v[62:65], v[98:101], v[158:161], v[62:65]
	v_mfma_f32_16x16x32_bf16 v[58:61], v[122:125], v[158:161], v[58:61]
	v_mfma_f32_16x16x32_bf16 v[46:49], v[98:101], v[170:173], v[46:49]
	v_mfma_f32_16x16x32_bf16 v[42:45], v[122:125], v[170:173], v[42:45]
	v_mfma_f32_16x16x32_bf16 v[30:33], v[98:101], v[178:181], v[30:33]
	v_mfma_f32_16x16x32_bf16 v[26:29], v[122:125], v[178:181], v[26:29]
	v_mfma_f32_16x16x32_bf16 v[14:17], v[98:101], v[186:189], v[14:17]
	v_mfma_f32_16x16x32_bf16 v[10:13], v[122:125], v[186:189], v[10:13]
	v_mfma_f32_16x16x32_bf16 v[62:65], v[110:113], v[166:169], v[62:65]
	v_mfma_f32_16x16x32_bf16 v[58:61], v[130:133], v[166:169], v[58:61]
	v_mfma_f32_16x16x32_bf16 v[46:49], v[110:113], v[174:177], v[46:49]
	v_mfma_f32_16x16x32_bf16 v[42:45], v[130:133], v[174:177], v[42:45]
	v_mfma_f32_16x16x32_bf16 v[30:33], v[110:113], v[182:185], v[30:33]
	v_mfma_f32_16x16x32_bf16 v[26:29], v[130:133], v[182:185], v[26:29]
	v_mfma_f32_16x16x32_bf16 v[14:17], v[110:113], v[190:193], v[14:17]
	v_mfma_f32_16x16x32_bf16 v[10:13], v[130:133], v[190:193], v[10:13]
	v_mfma_f32_16x16x32_bf16 v[54:57], v[138:141], v[158:161], v[54:57]
	v_mfma_f32_16x16x32_bf16 v[50:53], v[146:149], v[158:161], v[50:53]
	v_mfma_f32_16x16x32_bf16 v[38:41], v[138:141], v[170:173], v[38:41]
	v_mfma_f32_16x16x32_bf16 v[34:37], v[146:149], v[170:173], v[34:37]
	v_mfma_f32_16x16x32_bf16 v[22:25], v[138:141], v[178:181], v[22:25]
	v_mfma_f32_16x16x32_bf16 v[18:21], v[146:149], v[178:181], v[18:21]
	v_mfma_f32_16x16x32_bf16 v[6:9], v[138:141], v[186:189], v[6:9]
	v_mfma_f32_16x16x32_bf16 v[2:5], v[146:149], v[186:189], v[2:5]
	v_mfma_f32_16x16x32_bf16 v[54:57], v[142:145], v[166:169], v[54:57]
	v_mfma_f32_16x16x32_bf16 v[50:53], v[150:153], v[166:169], v[50:53]
	v_mfma_f32_16x16x32_bf16 v[38:41], v[142:145], v[174:177], v[38:41]
	v_mfma_f32_16x16x32_bf16 v[34:37], v[150:153], v[174:177], v[34:37]
	v_mfma_f32_16x16x32_bf16 v[22:25], v[142:145], v[182:185], v[22:25]
	v_mfma_f32_16x16x32_bf16 v[18:21], v[150:153], v[182:185], v[18:21]
	v_mfma_f32_16x16x32_bf16 v[6:9], v[142:145], v[190:193], v[6:9]
	v_mfma_f32_16x16x32_bf16 v[2:5], v[150:153], v[190:193], v[2:5]
	s_setprio 0
	s_barrier
	s_add_i32 s47, 0, 0x18000
	v_add_u32_e32 v0, s47, v242
	s_add_i32 s48, 0, 0x1c000
	ds_read_b128 v[98:101], v0
	ds_read_b128 v[110:113], v0 offset:1024
	ds_read_b128 v[122:125], v0 offset:2048
	ds_read_b128 v[130:133], v0 offset:3072
	v_add_u32_e32 v0, s48, v242
	ds_read_b128 v[138:141], v0
	ds_read_b128 v[142:145], v0 offset:1024
	ds_read_b128 v[146:149], v0 offset:2048
	ds_read_b128 v[150:153], v0 offset:3072
	s_add_u32 s18, s24, 0x40000
	s_addc_u32 s19, s25, 0
	s_mov_b32 m0, s29
	v_lshl_add_u64 v[216:217], s[18:19], 0, v[198:199]
	ds_read_b128 v[158:161], v247 offset:32768
	ds_read_b128 v[166:169], v247 offset:33792
	ds_read_b128 v[170:173], v247 offset:34816
	ds_read_b128 v[174:177], v247 offset:35840
	ds_read_b128 v[178:181], v247 offset:36864
	ds_read_b128 v[182:185], v247 offset:37888
	ds_read_b128 v[186:189], v247 offset:38912
	ds_read_b128 v[190:193], v247 offset:39936
	global_load_lds_dwordx4 v[216:217], off
	v_lshl_add_u64 v[216:217], s[18:19], 0, v[196:197]
	s_mov_b32 m0, s30
	s_nop 0
	global_load_lds_dwordx4 v[216:217], off
	s_waitcnt vmcnt(8)
	s_waitcnt lgkmcnt(0)
	s_barrier
	s_setprio 1
	v_mfma_f32_16x16x32_bf16 v[162:165], v[98:101], v[158:161], v[162:165]
	v_mfma_f32_16x16x32_bf16 v[154:157], v[122:125], v[158:161], v[154:157]
	v_mfma_f32_16x16x32_bf16 v[118:121], v[98:101], v[170:173], v[118:121]
	v_mfma_f32_16x16x32_bf16 v[114:117], v[122:125], v[170:173], v[114:117]
	v_mfma_f32_16x16x32_bf16 v[94:97], v[98:101], v[178:181], v[94:97]
	v_mfma_f32_16x16x32_bf16 v[90:93], v[122:125], v[178:181], v[90:93]
	v_mfma_f32_16x16x32_bf16 v[78:81], v[98:101], v[186:189], v[78:81]
	v_mfma_f32_16x16x32_bf16 v[74:77], v[122:125], v[186:189], v[74:77]
	v_mfma_f32_16x16x32_bf16 v[162:165], v[110:113], v[166:169], v[162:165]
	v_mfma_f32_16x16x32_bf16 v[154:157], v[130:133], v[166:169], v[154:157]
	v_mfma_f32_16x16x32_bf16 v[118:121], v[110:113], v[174:177], v[118:121]
	v_mfma_f32_16x16x32_bf16 v[114:117], v[130:133], v[174:177], v[114:117]
	v_mfma_f32_16x16x32_bf16 v[94:97], v[110:113], v[182:185], v[94:97]
	v_mfma_f32_16x16x32_bf16 v[90:93], v[130:133], v[182:185], v[90:93]
	v_mfma_f32_16x16x32_bf16 v[78:81], v[110:113], v[190:193], v[78:81]
	v_mfma_f32_16x16x32_bf16 v[74:77], v[130:133], v[190:193], v[74:77]
	v_mfma_f32_16x16x32_bf16 v[134:137], v[138:141], v[158:161], v[134:137]
	v_mfma_f32_16x16x32_bf16 v[126:129], v[146:149], v[158:161], v[126:129]
	v_mfma_f32_16x16x32_bf16 v[106:109], v[138:141], v[170:173], v[106:109]
	v_mfma_f32_16x16x32_bf16 v[102:105], v[146:149], v[170:173], v[102:105]
	v_mfma_f32_16x16x32_bf16 v[86:89], v[138:141], v[178:181], v[86:89]
	v_mfma_f32_16x16x32_bf16 v[82:85], v[146:149], v[178:181], v[82:85]
	v_mfma_f32_16x16x32_bf16 v[70:73], v[138:141], v[186:189], v[70:73]
	v_mfma_f32_16x16x32_bf16 v[66:69], v[146:149], v[186:189], v[66:69]
	v_mfma_f32_16x16x32_bf16 v[134:137], v[142:145], v[166:169], v[134:137]
	v_mfma_f32_16x16x32_bf16 v[126:129], v[150:153], v[166:169], v[126:129]
	v_mfma_f32_16x16x32_bf16 v[106:109], v[142:145], v[174:177], v[106:109]
	v_mfma_f32_16x16x32_bf16 v[102:105], v[150:153], v[174:177], v[102:105]
	v_mfma_f32_16x16x32_bf16 v[86:89], v[142:145], v[182:185], v[86:89]
	v_mfma_f32_16x16x32_bf16 v[82:85], v[150:153], v[182:185], v[82:85]
	v_mfma_f32_16x16x32_bf16 v[70:73], v[142:145], v[190:193], v[70:73]
	v_mfma_f32_16x16x32_bf16 v[66:69], v[150:153], v[190:193], v[66:69]
	s_setprio 0
	s_barrier
	s_add_i32 s18, s47, s26
	v_lshl_add_u64 v[208:209], v[208:209], 0, s[0:1]
	s_mov_b32 m0, s18
	ds_read_b128 v[158:161], v247 offset:49152
	ds_read_b128 v[166:169], v247 offset:50176
	ds_read_b128 v[170:173], v247 offset:51200
	ds_read_b128 v[174:177], v247 offset:52224
	ds_read_b128 v[178:181], v247 offset:53248
	ds_read_b128 v[182:185], v247 offset:54272
	ds_read_b128 v[186:189], v247 offset:55296
	ds_read_b128 v[190:193], v247 offset:56320
	global_load_lds_dwordx4 v[208:209], off
	s_add_i32 m0, s18, 0x2000
	s_add_u32 s18, s22, 0x40080
	v_lshl_add_u64 v[208:209], v[210:211], 0, s[0:1]
	s_addc_u32 s19, s23, 0
	s_add_i32 s22, s48, s26
	global_load_lds_dwordx4 v[208:209], off
	v_lshl_add_u64 v[208:209], s[18:19], 0, v[198:199]
	s_mov_b32 m0, s22
	s_nop 0
	global_load_lds_dwordx4 v[208:209], off
	v_lshl_add_u64 v[208:209], s[18:19], 0, v[196:197]
	s_add_i32 m0, s22, 0x2000
	s_nop 0
	global_load_lds_dwordx4 v[208:209], off
	v_lshl_add_u64 v[208:209], v[212:213], 0, s[0:1]
	s_mov_b32 m0, s34
	s_nop 0
	global_load_lds_dwordx4 v[208:209], off
	v_lshl_add_u64 v[208:209], v[214:215], 0, s[0:1]
	s_mov_b32 m0, s35
	s_nop 0
	global_load_lds_dwordx4 v[208:209], off
	s_waitcnt vmcnt(8)
	s_waitcnt lgkmcnt(0)
	s_barrier
	s_setprio 1
	v_mfma_f32_16x16x32_bf16 v[62:65], v[98:101], v[158:161], v[62:65]
	v_mfma_f32_16x16x32_bf16 v[58:61], v[122:125], v[158:161], v[58:61]
	v_mfma_f32_16x16x32_bf16 v[46:49], v[98:101], v[170:173], v[46:49]
	v_mfma_f32_16x16x32_bf16 v[42:45], v[122:125], v[170:173], v[42:45]
	v_mfma_f32_16x16x32_bf16 v[30:33], v[98:101], v[178:181], v[30:33]
	v_mfma_f32_16x16x32_bf16 v[26:29], v[122:125], v[178:181], v[26:29]
	v_mfma_f32_16x16x32_bf16 v[14:17], v[98:101], v[186:189], v[14:17]
	v_mfma_f32_16x16x32_bf16 v[10:13], v[122:125], v[186:189], v[10:13]
	v_mfma_f32_16x16x32_bf16 v[62:65], v[110:113], v[166:169], v[62:65]
	v_mfma_f32_16x16x32_bf16 v[58:61], v[130:133], v[166:169], v[58:61]
	v_mfma_f32_16x16x32_bf16 v[46:49], v[110:113], v[174:177], v[46:49]
	v_mfma_f32_16x16x32_bf16 v[42:45], v[130:133], v[174:177], v[42:45]
	v_mfma_f32_16x16x32_bf16 v[30:33], v[110:113], v[182:185], v[30:33]
	v_mfma_f32_16x16x32_bf16 v[26:29], v[130:133], v[182:185], v[26:29]
	v_mfma_f32_16x16x32_bf16 v[14:17], v[110:113], v[190:193], v[14:17]
	v_mfma_f32_16x16x32_bf16 v[10:13], v[130:133], v[190:193], v[10:13]
	v_mfma_f32_16x16x32_bf16 v[54:57], v[138:141], v[158:161], v[54:57]
	v_mfma_f32_16x16x32_bf16 v[50:53], v[146:149], v[158:161], v[50:53]
	v_mfma_f32_16x16x32_bf16 v[38:41], v[138:141], v[170:173], v[38:41]
	v_mfma_f32_16x16x32_bf16 v[34:37], v[146:149], v[170:173], v[34:37]
	v_mfma_f32_16x16x32_bf16 v[22:25], v[138:141], v[178:181], v[22:25]
	v_mfma_f32_16x16x32_bf16 v[18:21], v[146:149], v[178:181], v[18:21]
	v_mfma_f32_16x16x32_bf16 v[6:9], v[138:141], v[186:189], v[6:9]
	v_mfma_f32_16x16x32_bf16 v[2:5], v[146:149], v[186:189], v[2:5]
	v_mfma_f32_16x16x32_bf16 v[54:57], v[142:145], v[166:169], v[54:57]
	v_mfma_f32_16x16x32_bf16 v[50:53], v[150:153], v[166:169], v[50:53]
	v_mfma_f32_16x16x32_bf16 v[38:41], v[142:145], v[174:177], v[38:41]
	v_mfma_f32_16x16x32_bf16 v[34:37], v[150:153], v[174:177], v[34:37]
	v_mfma_f32_16x16x32_bf16 v[22:25], v[142:145], v[182:185], v[22:25]
	v_mfma_f32_16x16x32_bf16 v[18:21], v[150:153], v[182:185], v[18:21]
	v_mfma_f32_16x16x32_bf16 v[6:9], v[142:145], v[190:193], v[6:9]
	v_mfma_f32_16x16x32_bf16 v[2:5], v[150:153], v[190:193], v[2:5]
	s_setprio 0
	s_barrier
	s_add_i32 s46, s46, 2
	s_add_u32 s44, s44, 0x100
	s_addc_u32 s45, s45, 0
	s_cmp_gt_u32 s46, 13
	s_mov_b64 s[18:19], s[20:21]
	s_cbranch_scc0 .LBB0_106
	s_and_b64 vcc, exec, s[10:11]
	s_cbranch_vccz .LBB0_109
	s_barrier

.LBB0_611:
	s_add_u32 s22, s45, s20
	s_addc_u32 s23, s46, s21
	s_add_u32 s22, s22, 0x5000100
	s_addc_u32 s23, s23, 0
	s_add_u32 s50, s47, s20
	s_addc_u32 s51, s48, s21
	s_add_i32 s52, 0, 0x10000
	s_cmpk_eq_i32 s20, 0x700
	s_cselect_b32 s25, s42, s23
	s_cselect_b32 s24, s19, s22
	s_cselect_b32 s23, s44, s51
	s_cselect_b32 s22, s43, s50
	s_add_i32 s53, 0, 0x14000
	v_add_u32_e32 v160, s52, v144
	v_add_u32_e32 v176, s53, v144
	ds_read_b128 v[148:151], v160
	ds_read_b128 v[152:155], v160 offset:1024
	ds_read_b128 v[156:159], v160 offset:2048
	ds_read_b128 v[160:163], v160 offset:3072
	ds_read_b128 v[164:167], v176
	ds_read_b128 v[168:171], v176 offset:1024
	ds_read_b128 v[172:175], v176 offset:2048
	ds_read_b128 v[176:179], v176 offset:3072
	v_lshl_add_u64 v[192:193], v[138:139], 0, s[20:21]
	s_add_i32 m0, s27, 0xc000
	ds_read_b128 v[180:183], v147
	ds_read_b128 v[184:187], v147 offset:1024
	ds_read_b128 v[188:191], v147 offset:2048
	ds_read_b128 v[196:199], v147 offset:3072
	ds_read_b128 v[202:205], v147 offset:4096
	ds_read_b128 v[206:209], v147 offset:5120
	ds_read_b128 v[210:213], v147 offset:6144
	ds_read_b128 v[214:217], v147 offset:7168
	global_load_lds_dwordx4 v[192:193], off
	v_lshl_add_u64 v[192:193], v[140:141], 0, s[20:21]
	s_add_i32 m0, s27, 0xe000
	s_nop 0
	global_load_lds_dwordx4 v[192:193], off
	s_waitcnt vmcnt(8)
	s_waitcnt lgkmcnt(0)
	s_barrier
	s_setprio 1
	v_mfma_f32_16x16x32_bf16 v[126:129], v[148:151], v[180:183], v[126:129]
	v_mfma_f32_16x16x32_bf16 v[122:125], v[156:159], v[180:183], v[122:125]
	v_mfma_f32_16x16x32_bf16 v[114:117], v[148:151], v[188:191], v[114:117]
	v_mfma_f32_16x16x32_bf16 v[106:109], v[156:159], v[188:191], v[106:109]
	v_mfma_f32_16x16x32_bf16 v[98:101], v[148:151], v[202:205], v[98:101]
	v_mfma_f32_16x16x32_bf16 v[90:93], v[156:159], v[202:205], v[90:93]
	v_mfma_f32_16x16x32_bf16 v[82:85], v[148:151], v[210:213], v[82:85]
	v_mfma_f32_16x16x32_bf16 v[74:77], v[156:159], v[210:213], v[74:77]
	v_mfma_f32_16x16x32_bf16 v[126:129], v[152:155], v[184:187], v[126:129]
	v_mfma_f32_16x16x32_bf16 v[122:125], v[160:163], v[184:187], v[122:125]
	v_mfma_f32_16x16x32_bf16 v[114:117], v[152:155], v[196:199], v[114:117]
	v_mfma_f32_16x16x32_bf16 v[106:109], v[160:163], v[196:199], v[106:109]
	v_mfma_f32_16x16x32_bf16 v[98:101], v[152:155], v[206:209], v[98:101]
	v_mfma_f32_16x16x32_bf16 v[90:93], v[160:163], v[206:209], v[90:93]
	v_mfma_f32_16x16x32_bf16 v[82:85], v[152:155], v[214:217], v[82:85]
	v_mfma_f32_16x16x32_bf16 v[74:77], v[160:163], v[214:217], v[74:77]
	v_mfma_f32_16x16x32_bf16 v[118:121], v[164:167], v[180:183], v[118:121]
	v_mfma_f32_16x16x32_bf16 v[110:113], v[172:175], v[180:183], v[110:113]
	v_mfma_f32_16x16x32_bf16 v[102:105], v[164:167], v[188:191], v[102:105]
	v_mfma_f32_16x16x32_bf16 v[94:97], v[172:175], v[188:191], v[94:97]
	v_mfma_f32_16x16x32_bf16 v[86:89], v[164:167], v[202:205], v[86:89]
	v_mfma_f32_16x16x32_bf16 v[78:81], v[172:175], v[202:205], v[78:81]
	v_mfma_f32_16x16x32_bf16 v[70:73], v[164:167], v[210:213], v[70:73]
	v_mfma_f32_16x16x32_bf16 v[66:69], v[172:175], v[210:213], v[66:69]
	v_mfma_f32_16x16x32_bf16 v[118:121], v[168:171], v[184:187], v[118:121]
	v_mfma_f32_16x16x32_bf16 v[110:113], v[176:179], v[184:187], v[110:113]
	v_mfma_f32_16x16x32_bf16 v[102:105], v[168:171], v[196:199], v[102:105]
	v_mfma_f32_16x16x32_bf16 v[94:97], v[176:179], v[196:199], v[94:97]
	v_mfma_f32_16x16x32_bf16 v[86:89], v[168:171], v[206:209], v[86:89]
	v_mfma_f32_16x16x32_bf16 v[78:81], v[176:179], v[206:209], v[78:81]
	v_mfma_f32_16x16x32_bf16 v[70:73], v[168:171], v[214:217], v[70:73]
	v_mfma_f32_16x16x32_bf16 v[66:69], v[176:179], v[214:217], v[66:69]
	s_setprio 0
	s_barrier
	s_add_i32 s50, s52, s26
	v_lshl_add_u64 v[192:193], s[22:23], 0, v[130:131]
	s_mov_b32 m0, s50
	ds_read_b128 v[180:183], v147 offset:16384
	ds_read_b128 v[184:187], v147 offset:17408
	ds_read_b128 v[188:191], v147 offset:18432
	ds_read_b128 v[196:199], v147 offset:19456
	ds_read_b128 v[202:205], v147 offset:20480
	ds_read_b128 v[206:209], v147 offset:21504
	ds_read_b128 v[210:213], v147 offset:22528
	ds_read_b128 v[214:217], v147 offset:23552
	global_load_lds_dwordx4 v[192:193], off
	s_add_i32 m0, s50, 0x2000
	s_add_u32 s50, s22, 0x40000
	v_lshl_add_u64 v[218:219], s[22:23], 0, v[132:133]
	s_addc_u32 s51, s23, 0
	s_add_i32 s52, s53, s26
	global_load_lds_dwordx4 v[218:219], off
	v_lshl_add_u64 v[220:221], s[50:51], 0, v[130:131]
	s_mov_b32 m0, s52
	v_lshl_add_u64 v[222:223], s[24:25], 0, v[132:133]
	global_load_lds_dwordx4 v[220:221], off
	v_lshl_add_u64 v[220:221], s[50:51], 0, v[132:133]
	s_add_i32 m0, s52, 0x2000
	s_nop 0
	global_load_lds_dwordx4 v[220:221], off
	v_lshl_add_u64 v[220:221], s[24:25], 0, v[130:131]
	s_mov_b32 m0, s27
	s_nop 0
	global_load_lds_dwordx4 v[220:221], off
	s_mov_b32 m0, s28
	s_nop 0
	global_load_lds_dwordx4 v[222:223], off
	s_waitcnt vmcnt(8)
	s_waitcnt lgkmcnt(0)
	s_barrier
	s_setprio 1
	v_mfma_f32_16x16x32_bf16 v[62:65], v[148:151], v[180:183], v[62:65]
	v_mfma_f32_16x16x32_bf16 v[58:61], v[156:159], v[180:183], v[58:61]
	v_mfma_f32_16x16x32_bf16 v[50:53], v[148:151], v[188:191], v[50:53]
	v_mfma_f32_16x16x32_bf16 v[42:45], v[156:159], v[188:191], v[42:45]
	v_mfma_f32_16x16x32_bf16 v[34:37], v[148:151], v[202:205], v[34:37]
	v_mfma_f32_16x16x32_bf16 v[26:29], v[156:159], v[202:205], v[26:29]
	v_mfma_f32_16x16x32_bf16 v[18:21], v[148:151], v[210:213], v[18:21]
	v_mfma_f32_16x16x32_bf16 v[10:13], v[156:159], v[210:213], v[10:13]
	v_mfma_f32_16x16x32_bf16 v[62:65], v[152:155], v[184:187], v[62:65]
	v_mfma_f32_16x16x32_bf16 v[58:61], v[160:163], v[184:187], v[58:61]
	v_mfma_f32_16x16x32_bf16 v[50:53], v[152:155], v[196:199], v[50:53]
	v_mfma_f32_16x16x32_bf16 v[42:45], v[160:163], v[196:199], v[42:45]
	v_mfma_f32_16x16x32_bf16 v[34:37], v[152:155], v[206:209], v[34:37]
	v_mfma_f32_16x16x32_bf16 v[26:29], v[160:163], v[206:209], v[26:29]
	v_mfma_f32_16x16x32_bf16 v[18:21], v[152:155], v[214:217], v[18:21]
	v_mfma_f32_16x16x32_bf16 v[10:13], v[160:163], v[214:217], v[10:13]
	v_mfma_f32_16x16x32_bf16 v[54:57], v[164:167], v[180:183], v[54:57]
	v_mfma_f32_16x16x32_bf16 v[46:49], v[172:175], v[180:183], v[46:49]
	v_mfma_f32_16x16x32_bf16 v[38:41], v[164:167], v[188:191], v[38:41]
	v_mfma_f32_16x16x32_bf16 v[30:33], v[172:175], v[188:191], v[30:33]
	v_mfma_f32_16x16x32_bf16 v[22:25], v[164:167], v[202:205], v[22:25]
	v_mfma_f32_16x16x32_bf16 v[14:17], v[172:175], v[202:205], v[14:17]
	v_mfma_f32_16x16x32_bf16 v[6:9], v[164:167], v[210:213], v[6:9]
	v_mfma_f32_16x16x32_bf16 v[2:5], v[172:175], v[210:213], v[2:5]
	v_mfma_f32_16x16x32_bf16 v[54:57], v[168:171], v[184:187], v[54:57]
	v_mfma_f32_16x16x32_bf16 v[46:49], v[176:179], v[184:187], v[46:49]
	v_mfma_f32_16x16x32_bf16 v[38:41], v[168:171], v[196:199], v[38:41]
	v_mfma_f32_16x16x32_bf16 v[30:33], v[176:179], v[196:199], v[30:33]
	v_mfma_f32_16x16x32_bf16 v[22:25], v[168:171], v[206:209], v[22:25]
	v_mfma_f32_16x16x32_bf16 v[14:17], v[176:179], v[206:209], v[14:17]
	v_mfma_f32_16x16x32_bf16 v[6:9], v[168:171], v[214:217], v[6:9]
	v_mfma_f32_16x16x32_bf16 v[2:5], v[176:179], v[214:217], v[2:5]
	s_setprio 0
	s_barrier
	s_add_i32 s50, 0, 0x18000
	s_add_i32 s51, 0, 0x1c000
	v_add_u32_e32 v160, s50, v144
	v_add_u32_e32 v176, s51, v144
	ds_read_b128 v[148:151], v160
	ds_read_b128 v[152:155], v160 offset:1024
	ds_read_b128 v[156:159], v160 offset:2048
	ds_read_b128 v[160:163], v160 offset:3072
	ds_read_b128 v[164:167], v176
	ds_read_b128 v[168:171], v176 offset:1024
	ds_read_b128 v[172:175], v176 offset:2048
	ds_read_b128 v[176:179], v176 offset:3072
	s_add_u32 s24, s24, 0x40000
	s_addc_u32 s25, s25, 0
	s_mov_b32 m0, s29
	v_lshl_add_u64 v[224:225], s[24:25], 0, v[130:131]
	ds_read_b128 v[180:183], v147 offset:32768
	ds_read_b128 v[184:187], v147 offset:33792
	ds_read_b128 v[188:191], v147 offset:34816
	ds_read_b128 v[196:199], v147 offset:35840
	ds_read_b128 v[202:205], v147 offset:36864
	ds_read_b128 v[206:209], v147 offset:37888
	ds_read_b128 v[210:213], v147 offset:38912
	ds_read_b128 v[214:217], v147 offset:39936
	global_load_lds_dwordx4 v[224:225], off
	v_lshl_add_u64 v[224:225], s[24:25], 0, v[132:133]
	s_mov_b32 m0, s30
	s_nop 0
	global_load_lds_dwordx4 v[224:225], off
	s_waitcnt vmcnt(8)
	s_waitcnt lgkmcnt(0)
	s_barrier
	s_setprio 1
	v_mfma_f32_16x16x32_bf16 v[126:129], v[148:151], v[180:183], v[126:129]
	v_mfma_f32_16x16x32_bf16 v[122:125], v[156:159], v[180:183], v[122:125]
	v_mfma_f32_16x16x32_bf16 v[114:117], v[148:151], v[188:191], v[114:117]
	v_mfma_f32_16x16x32_bf16 v[106:109], v[156:159], v[188:191], v[106:109]
	v_mfma_f32_16x16x32_bf16 v[98:101], v[148:151], v[202:205], v[98:101]
	v_mfma_f32_16x16x32_bf16 v[90:93], v[156:159], v[202:205], v[90:93]
	v_mfma_f32_16x16x32_bf16 v[82:85], v[148:151], v[210:213], v[82:85]
	v_mfma_f32_16x16x32_bf16 v[74:77], v[156:159], v[210:213], v[74:77]
	v_mfma_f32_16x16x32_bf16 v[126:129], v[152:155], v[184:187], v[126:129]
	v_mfma_f32_16x16x32_bf16 v[122:125], v[160:163], v[184:187], v[122:125]
	v_mfma_f32_16x16x32_bf16 v[114:117], v[152:155], v[196:199], v[114:117]
	v_mfma_f32_16x16x32_bf16 v[106:109], v[160:163], v[196:199], v[106:109]
	v_mfma_f32_16x16x32_bf16 v[98:101], v[152:155], v[206:209], v[98:101]
	v_mfma_f32_16x16x32_bf16 v[90:93], v[160:163], v[206:209], v[90:93]
	v_mfma_f32_16x16x32_bf16 v[82:85], v[152:155], v[214:217], v[82:85]
	v_mfma_f32_16x16x32_bf16 v[74:77], v[160:163], v[214:217], v[74:77]
	v_mfma_f32_16x16x32_bf16 v[118:121], v[164:167], v[180:183], v[118:121]
	v_mfma_f32_16x16x32_bf16 v[110:113], v[172:175], v[180:183], v[110:113]
	v_mfma_f32_16x16x32_bf16 v[102:105], v[164:167], v[188:191], v[102:105]
	v_mfma_f32_16x16x32_bf16 v[94:97], v[172:175], v[188:191], v[94:97]
	v_mfma_f32_16x16x32_bf16 v[86:89], v[164:167], v[202:205], v[86:89]
	v_mfma_f32_16x16x32_bf16 v[78:81], v[172:175], v[202:205], v[78:81]
	v_mfma_f32_16x16x32_bf16 v[70:73], v[164:167], v[210:213], v[70:73]
	v_mfma_f32_16x16x32_bf16 v[66:69], v[172:175], v[210:213], v[66:69]
	v_mfma_f32_16x16x32_bf16 v[118:121], v[168:171], v[184:187], v[118:121]
	v_mfma_f32_16x16x32_bf16 v[110:113], v[176:179], v[184:187], v[110:113]
	v_mfma_f32_16x16x32_bf16 v[102:105], v[168:171], v[196:199], v[102:105]
	v_mfma_f32_16x16x32_bf16 v[94:97], v[176:179], v[196:199], v[94:97]
	v_mfma_f32_16x16x32_bf16 v[86:89], v[168:171], v[206:209], v[86:89]
	v_mfma_f32_16x16x32_bf16 v[78:81], v[176:179], v[206:209], v[78:81]
	v_mfma_f32_16x16x32_bf16 v[70:73], v[168:171], v[214:217], v[70:73]
	v_mfma_f32_16x16x32_bf16 v[66:69], v[176:179], v[214:217], v[66:69]
	s_setprio 0
	s_barrier
	s_add_i32 s24, s50, s26
	v_lshl_add_u64 v[192:193], v[192:193], 0, s[0:1]
	s_mov_b32 m0, s24
	ds_read_b128 v[180:183], v147 offset:49152
	ds_read_b128 v[184:187], v147 offset:50176
	ds_read_b128 v[188:191], v147 offset:51200
	ds_read_b128 v[196:199], v147 offset:52224
	ds_read_b128 v[202:205], v147 offset:53248
	ds_read_b128 v[206:209], v147 offset:54272
	ds_read_b128 v[210:213], v147 offset:55296
	ds_read_b128 v[214:217], v147 offset:56320
	global_load_lds_dwordx4 v[192:193], off
	s_add_i32 m0, s24, 0x2000
	s_add_u32 s22, s22, 0x40080
	v_lshl_add_u64 v[192:193], v[218:219], 0, s[0:1]
	s_addc_u32 s23, s23, 0
	s_add_i32 s24, s51, s26
	global_load_lds_dwordx4 v[192:193], off
	v_lshl_add_u64 v[192:193], s[22:23], 0, v[130:131]
	s_mov_b32 m0, s24
	s_nop 0
	global_load_lds_dwordx4 v[192:193], off
	v_lshl_add_u64 v[192:193], s[22:23], 0, v[132:133]
	s_add_i32 m0, s24, 0x2000
	s_nop 0
	global_load_lds_dwordx4 v[192:193], off
	v_lshl_add_u64 v[192:193], v[220:221], 0, s[0:1]
	s_mov_b32 m0, s31
	s_nop 0
	global_load_lds_dwordx4 v[192:193], off
	v_lshl_add_u64 v[192:193], v[222:223], 0, s[0:1]
	s_mov_b32 m0, s33
	s_nop 0
	global_load_lds_dwordx4 v[192:193], off
	s_waitcnt vmcnt(8)
	s_waitcnt lgkmcnt(0)
	s_barrier
	s_setprio 1
	v_mfma_f32_16x16x32_bf16 v[62:65], v[148:151], v[180:183], v[62:65]
	v_mfma_f32_16x16x32_bf16 v[58:61], v[156:159], v[180:183], v[58:61]
	v_mfma_f32_16x16x32_bf16 v[50:53], v[148:151], v[188:191], v[50:53]
	v_mfma_f32_16x16x32_bf16 v[42:45], v[156:159], v[188:191], v[42:45]
	v_mfma_f32_16x16x32_bf16 v[34:37], v[148:151], v[202:205], v[34:37]
	v_mfma_f32_16x16x32_bf16 v[26:29], v[156:159], v[202:205], v[26:29]
	v_mfma_f32_16x16x32_bf16 v[18:21], v[148:151], v[210:213], v[18:21]
	v_mfma_f32_16x16x32_bf16 v[10:13], v[156:159], v[210:213], v[10:13]
	v_mfma_f32_16x16x32_bf16 v[62:65], v[152:155], v[184:187], v[62:65]
	v_mfma_f32_16x16x32_bf16 v[58:61], v[160:163], v[184:187], v[58:61]
	v_mfma_f32_16x16x32_bf16 v[50:53], v[152:155], v[196:199], v[50:53]
	v_mfma_f32_16x16x32_bf16 v[42:45], v[160:163], v[196:199], v[42:45]
	v_mfma_f32_16x16x32_bf16 v[34:37], v[152:155], v[206:209], v[34:37]
	v_mfma_f32_16x16x32_bf16 v[26:29], v[160:163], v[206:209], v[26:29]
	v_mfma_f32_16x16x32_bf16 v[18:21], v[152:155], v[214:217], v[18:21]
	v_mfma_f32_16x16x32_bf16 v[10:13], v[160:163], v[214:217], v[10:13]
	v_mfma_f32_16x16x32_bf16 v[54:57], v[164:167], v[180:183], v[54:57]
	v_mfma_f32_16x16x32_bf16 v[46:49], v[172:175], v[180:183], v[46:49]
	v_mfma_f32_16x16x32_bf16 v[38:41], v[164:167], v[188:191], v[38:41]
	v_mfma_f32_16x16x32_bf16 v[30:33], v[172:175], v[188:191], v[30:33]
	v_mfma_f32_16x16x32_bf16 v[22:25], v[164:167], v[202:205], v[22:25]
	v_mfma_f32_16x16x32_bf16 v[14:17], v[172:175], v[202:205], v[14:17]
	v_mfma_f32_16x16x32_bf16 v[6:9], v[164:167], v[210:213], v[6:9]
	v_mfma_f32_16x16x32_bf16 v[2:5], v[172:175], v[210:213], v[2:5]
	v_mfma_f32_16x16x32_bf16 v[54:57], v[168:171], v[184:187], v[54:57]
	v_mfma_f32_16x16x32_bf16 v[46:49], v[176:179], v[184:187], v[46:49]
	v_mfma_f32_16x16x32_bf16 v[38:41], v[168:171], v[196:199], v[38:41]
	v_mfma_f32_16x16x32_bf16 v[30:33], v[176:179], v[196:199], v[30:33]
	v_mfma_f32_16x16x32_bf16 v[22:25], v[168:171], v[206:209], v[22:25]
	v_mfma_f32_16x16x32_bf16 v[14:17], v[176:179], v[206:209], v[14:17]
	v_mfma_f32_16x16x32_bf16 v[6:9], v[168:171], v[214:217], v[6:9]
	v_mfma_f32_16x16x32_bf16 v[2:5], v[176:179], v[214:217], v[2:5]
	s_setprio 0
	s_barrier
	s_add_i32 s49, s49, 2
	s_add_u32 s20, s20, 0x100
	s_addc_u32 s21, s21, 0
	s_cmp_gt_u32 s49, 13
	s_cbranch_scc0 .LBB0_611
	s_and_b64 vcc, exec, s[10:11]
	s_cbranch_vccz .LBB0_614
	s_barrier

.LBB0_636:
	s_add_u32 s20, s18, 0x100
	s_addc_u32 s21, s19, 0
	s_add_i32 s47, 0, 0x10000
	s_cmp_eq_u32 s46, 40
	s_cselect_b32 s25, s15, s21
	s_cselect_b32 s24, s14, s20
	v_add_u32_e32 v0, s47, v242
	s_cselect_b32 s23, s43, s45
	s_cselect_b32 s22, s42, s44
	s_add_i32 s48, 0, 0x14000
	ds_read_b128 v[90:93], v0
	ds_read_b128 v[102:105], v0 offset:1024
	ds_read_b128 v[114:117], v0 offset:2048
	ds_read_b128 v[122:125], v0 offset:3072
	v_add_u32_e32 v0, s48, v242
	ds_read_b128 v[130:133], v0
	ds_read_b128 v[142:145], v0 offset:1024
	ds_read_b128 v[146:149], v0 offset:2048
	ds_read_b128 v[150:153], v0 offset:3072
	v_lshl_add_u64 v[208:209], s[18:19], 0, v[204:205]
	s_add_i32 m0, s27, 0xc000
	ds_read_b128 v[154:157], v247
	ds_read_b128 v[162:165], v247 offset:1024
	ds_read_b128 v[170:173], v247 offset:2048
	ds_read_b128 v[174:177], v247 offset:3072
	ds_read_b128 v[178:181], v247 offset:4096
	ds_read_b128 v[182:185], v247 offset:5120
	ds_read_b128 v[186:189], v247 offset:6144
	ds_read_b128 v[190:193], v247 offset:7168
	global_load_lds_dwordx4 v[208:209], off
	v_lshl_add_u64 v[208:209], s[18:19], 0, v[206:207]
	s_add_i32 m0, s27, 0xe000
	s_nop 0
	global_load_lds_dwordx4 v[208:209], off
	s_waitcnt vmcnt(8)
	s_waitcnt lgkmcnt(0)
	s_barrier
	s_setprio 1
	v_mfma_f32_16x16x32_bf16 v[166:169], v[90:93], v[154:157], v[166:169]
	v_mfma_f32_16x16x32_bf16 v[158:161], v[114:117], v[154:157], v[158:161]
	v_mfma_f32_16x16x32_bf16 v[126:129], v[90:93], v[170:173], v[126:129]
	v_mfma_f32_16x16x32_bf16 v[118:121], v[114:117], v[170:173], v[118:121]
	v_mfma_f32_16x16x32_bf16 v[98:101], v[90:93], v[178:181], v[98:101]
	v_mfma_f32_16x16x32_bf16 v[94:97], v[114:117], v[178:181], v[94:97]
	v_mfma_f32_16x16x32_bf16 v[78:81], v[90:93], v[186:189], v[78:81]
	v_mfma_f32_16x16x32_bf16 v[74:77], v[114:117], v[186:189], v[74:77]
	v_mfma_f32_16x16x32_bf16 v[166:169], v[102:105], v[162:165], v[166:169]
	v_mfma_f32_16x16x32_bf16 v[158:161], v[122:125], v[162:165], v[158:161]
	v_mfma_f32_16x16x32_bf16 v[126:129], v[102:105], v[174:177], v[126:129]
	v_mfma_f32_16x16x32_bf16 v[118:121], v[122:125], v[174:177], v[118:121]
	v_mfma_f32_16x16x32_bf16 v[98:101], v[102:105], v[182:185], v[98:101]
	v_mfma_f32_16x16x32_bf16 v[94:97], v[122:125], v[182:185], v[94:97]
	v_mfma_f32_16x16x32_bf16 v[78:81], v[102:105], v[190:193], v[78:81]
	v_mfma_f32_16x16x32_bf16 v[74:77], v[122:125], v[190:193], v[74:77]
	v_mfma_f32_16x16x32_bf16 v[138:141], v[130:133], v[154:157], v[138:141]
	v_mfma_f32_16x16x32_bf16 v[134:137], v[146:149], v[154:157], v[134:137]
	v_mfma_f32_16x16x32_bf16 v[110:113], v[130:133], v[170:173], v[110:113]
	v_mfma_f32_16x16x32_bf16 v[106:109], v[146:149], v[170:173], v[106:109]
	v_mfma_f32_16x16x32_bf16 v[86:89], v[130:133], v[178:181], v[86:89]
	v_mfma_f32_16x16x32_bf16 v[82:85], v[146:149], v[178:181], v[82:85]
	v_mfma_f32_16x16x32_bf16 v[70:73], v[130:133], v[186:189], v[70:73]
	v_mfma_f32_16x16x32_bf16 v[66:69], v[146:149], v[186:189], v[66:69]
	v_mfma_f32_16x16x32_bf16 v[138:141], v[142:145], v[162:165], v[138:141]
	v_mfma_f32_16x16x32_bf16 v[134:137], v[150:153], v[162:165], v[134:137]
	v_mfma_f32_16x16x32_bf16 v[110:113], v[142:145], v[174:177], v[110:113]
	v_mfma_f32_16x16x32_bf16 v[106:109], v[150:153], v[174:177], v[106:109]
	v_mfma_f32_16x16x32_bf16 v[86:89], v[142:145], v[182:185], v[86:89]
	v_mfma_f32_16x16x32_bf16 v[82:85], v[150:153], v[182:185], v[82:85]
	v_mfma_f32_16x16x32_bf16 v[70:73], v[142:145], v[190:193], v[70:73]
	v_mfma_f32_16x16x32_bf16 v[66:69], v[150:153], v[190:193], v[66:69]
	s_setprio 0
	s_barrier
	s_add_i32 s18, s47, s26
	v_lshl_add_u64 v[208:209], s[22:23], 0, v[198:199]
	s_mov_b32 m0, s18
	ds_read_b128 v[154:157], v247 offset:16384
	ds_read_b128 v[162:165], v247 offset:17408
	ds_read_b128 v[170:173], v247 offset:18432
	ds_read_b128 v[174:177], v247 offset:19456
	ds_read_b128 v[178:181], v247 offset:20480
	ds_read_b128 v[182:185], v247 offset:21504
	ds_read_b128 v[186:189], v247 offset:22528
	ds_read_b128 v[190:193], v247 offset:23552
	global_load_lds_dwordx4 v[208:209], off
	s_add_i32 m0, s18, 0x2000
	s_add_u32 s18, s22, 0xb0000
	v_lshl_add_u64 v[210:211], s[22:23], 0, v[196:197]
	s_addc_u32 s19, s23, 0
	s_add_i32 s47, s48, s26
	global_load_lds_dwordx4 v[210:211], off
	v_lshl_add_u64 v[212:213], s[18:19], 0, v[198:199]
	s_mov_b32 m0, s47
	v_lshl_add_u64 v[214:215], s[24:25], 0, v[196:197]
	global_load_lds_dwordx4 v[212:213], off
	v_lshl_add_u64 v[212:213], s[18:19], 0, v[196:197]
	s_add_i32 m0, s47, 0x2000
	s_nop 0
	global_load_lds_dwordx4 v[212:213], off
	v_lshl_add_u64 v[212:213], s[24:25], 0, v[198:199]
	s_mov_b32 m0, s27
	s_nop 0
	global_load_lds_dwordx4 v[212:213], off
	s_mov_b32 m0, s28
	s_nop 0
	global_load_lds_dwordx4 v[214:215], off
	s_waitcnt vmcnt(8)
	s_waitcnt lgkmcnt(0)
	s_barrier
	s_setprio 1
	v_mfma_f32_16x16x32_bf16 v[62:65], v[90:93], v[154:157], v[62:65]
	v_mfma_f32_16x16x32_bf16 v[58:61], v[114:117], v[154:157], v[58:61]
	v_mfma_f32_16x16x32_bf16 v[46:49], v[90:93], v[170:173], v[46:49]
	v_mfma_f32_16x16x32_bf16 v[42:45], v[114:117], v[170:173], v[42:45]
	v_mfma_f32_16x16x32_bf16 v[30:33], v[90:93], v[178:181], v[30:33]
	v_mfma_f32_16x16x32_bf16 v[26:29], v[114:117], v[178:181], v[26:29]
	v_mfma_f32_16x16x32_bf16 v[14:17], v[90:93], v[186:189], v[14:17]
	v_mfma_f32_16x16x32_bf16 v[10:13], v[114:117], v[186:189], v[10:13]
	v_mfma_f32_16x16x32_bf16 v[62:65], v[102:105], v[162:165], v[62:65]
	v_mfma_f32_16x16x32_bf16 v[58:61], v[122:125], v[162:165], v[58:61]
	v_mfma_f32_16x16x32_bf16 v[46:49], v[102:105], v[174:177], v[46:49]
	v_mfma_f32_16x16x32_bf16 v[42:45], v[122:125], v[174:177], v[42:45]
	v_mfma_f32_16x16x32_bf16 v[30:33], v[102:105], v[182:185], v[30:33]
	v_mfma_f32_16x16x32_bf16 v[26:29], v[122:125], v[182:185], v[26:29]
	v_mfma_f32_16x16x32_bf16 v[14:17], v[102:105], v[190:193], v[14:17]
	v_mfma_f32_16x16x32_bf16 v[10:13], v[122:125], v[190:193], v[10:13]
	v_mfma_f32_16x16x32_bf16 v[54:57], v[130:133], v[154:157], v[54:57]
	v_mfma_f32_16x16x32_bf16 v[50:53], v[146:149], v[154:157], v[50:53]
	v_mfma_f32_16x16x32_bf16 v[38:41], v[130:133], v[170:173], v[38:41]
	v_mfma_f32_16x16x32_bf16 v[34:37], v[146:149], v[170:173], v[34:37]
	v_mfma_f32_16x16x32_bf16 v[22:25], v[130:133], v[178:181], v[22:25]
	v_mfma_f32_16x16x32_bf16 v[18:21], v[146:149], v[178:181], v[18:21]
	v_mfma_f32_16x16x32_bf16 v[6:9], v[130:133], v[186:189], v[6:9]
	v_mfma_f32_16x16x32_bf16 v[2:5], v[146:149], v[186:189], v[2:5]
	v_mfma_f32_16x16x32_bf16 v[54:57], v[142:145], v[162:165], v[54:57]
	v_mfma_f32_16x16x32_bf16 v[50:53], v[150:153], v[162:165], v[50:53]
	v_mfma_f32_16x16x32_bf16 v[38:41], v[142:145], v[174:177], v[38:41]
	v_mfma_f32_16x16x32_bf16 v[34:37], v[150:153], v[174:177], v[34:37]
	v_mfma_f32_16x16x32_bf16 v[22:25], v[142:145], v[182:185], v[22:25]
	v_mfma_f32_16x16x32_bf16 v[18:21], v[150:153], v[182:185], v[18:21]
	v_mfma_f32_16x16x32_bf16 v[6:9], v[142:145], v[190:193], v[6:9]
	v_mfma_f32_16x16x32_bf16 v[2:5], v[150:153], v[190:193], v[2:5]
	s_setprio 0
	s_barrier
	s_add_i32 s47, 0, 0x18000
	v_add_u32_e32 v0, s47, v242
	s_add_i32 s48, 0, 0x1c000
	ds_read_b128 v[90:93], v0
	ds_read_b128 v[102:105], v0 offset:1024
	ds_read_b128 v[114:117], v0 offset:2048
	ds_read_b128 v[122:125], v0 offset:3072
	v_add_u32_e32 v0, s48, v242
	ds_read_b128 v[130:133], v0
	ds_read_b128 v[142:145], v0 offset:1024
	ds_read_b128 v[146:149], v0 offset:2048
	ds_read_b128 v[150:153], v0 offset:3072
	s_add_u32 s18, s24, 0xb0000
	s_addc_u32 s19, s25, 0
	s_mov_b32 m0, s29
	v_lshl_add_u64 v[216:217], s[18:19], 0, v[198:199]
	ds_read_b128 v[154:157], v247 offset:32768
	ds_read_b128 v[162:165], v247 offset:33792
	ds_read_b128 v[170:173], v247 offset:34816
	ds_read_b128 v[174:177], v247 offset:35840
	ds_read_b128 v[178:181], v247 offset:36864
	ds_read_b128 v[182:185], v247 offset:37888
	ds_read_b128 v[186:189], v247 offset:38912
	ds_read_b128 v[190:193], v247 offset:39936
	global_load_lds_dwordx4 v[216:217], off
	v_lshl_add_u64 v[216:217], s[18:19], 0, v[196:197]
	s_mov_b32 m0, s30
	s_nop 0
	global_load_lds_dwordx4 v[216:217], off
	s_waitcnt vmcnt(8)
	s_waitcnt lgkmcnt(0)
	s_barrier
	s_setprio 1
	v_mfma_f32_16x16x32_bf16 v[166:169], v[90:93], v[154:157], v[166:169]
	v_mfma_f32_16x16x32_bf16 v[158:161], v[114:117], v[154:157], v[158:161]
	v_mfma_f32_16x16x32_bf16 v[126:129], v[90:93], v[170:173], v[126:129]
	v_mfma_f32_16x16x32_bf16 v[118:121], v[114:117], v[170:173], v[118:121]
	v_mfma_f32_16x16x32_bf16 v[98:101], v[90:93], v[178:181], v[98:101]
	v_mfma_f32_16x16x32_bf16 v[94:97], v[114:117], v[178:181], v[94:97]
	v_mfma_f32_16x16x32_bf16 v[78:81], v[90:93], v[186:189], v[78:81]
	v_mfma_f32_16x16x32_bf16 v[74:77], v[114:117], v[186:189], v[74:77]
	v_mfma_f32_16x16x32_bf16 v[166:169], v[102:105], v[162:165], v[166:169]
	v_mfma_f32_16x16x32_bf16 v[158:161], v[122:125], v[162:165], v[158:161]
	v_mfma_f32_16x16x32_bf16 v[126:129], v[102:105], v[174:177], v[126:129]
	v_mfma_f32_16x16x32_bf16 v[118:121], v[122:125], v[174:177], v[118:121]
	v_mfma_f32_16x16x32_bf16 v[98:101], v[102:105], v[182:185], v[98:101]
	v_mfma_f32_16x16x32_bf16 v[94:97], v[122:125], v[182:185], v[94:97]
	v_mfma_f32_16x16x32_bf16 v[78:81], v[102:105], v[190:193], v[78:81]
	v_mfma_f32_16x16x32_bf16 v[74:77], v[122:125], v[190:193], v[74:77]
	v_mfma_f32_16x16x32_bf16 v[138:141], v[130:133], v[154:157], v[138:141]
	v_mfma_f32_16x16x32_bf16 v[134:137], v[146:149], v[154:157], v[134:137]
	v_mfma_f32_16x16x32_bf16 v[110:113], v[130:133], v[170:173], v[110:113]
	v_mfma_f32_16x16x32_bf16 v[106:109], v[146:149], v[170:173], v[106:109]
	v_mfma_f32_16x16x32_bf16 v[86:89], v[130:133], v[178:181], v[86:89]
	v_mfma_f32_16x16x32_bf16 v[82:85], v[146:149], v[178:181], v[82:85]
	v_mfma_f32_16x16x32_bf16 v[70:73], v[130:133], v[186:189], v[70:73]
	v_mfma_f32_16x16x32_bf16 v[66:69], v[146:149], v[186:189], v[66:69]
	v_mfma_f32_16x16x32_bf16 v[138:141], v[142:145], v[162:165], v[138:141]
	v_mfma_f32_16x16x32_bf16 v[134:137], v[150:153], v[162:165], v[134:137]
	v_mfma_f32_16x16x32_bf16 v[110:113], v[142:145], v[174:177], v[110:113]
	v_mfma_f32_16x16x32_bf16 v[106:109], v[150:153], v[174:177], v[106:109]
	v_mfma_f32_16x16x32_bf16 v[86:89], v[142:145], v[182:185], v[86:89]
	v_mfma_f32_16x16x32_bf16 v[82:85], v[150:153], v[182:185], v[82:85]
	v_mfma_f32_16x16x32_bf16 v[70:73], v[142:145], v[190:193], v[70:73]
	v_mfma_f32_16x16x32_bf16 v[66:69], v[150:153], v[190:193], v[66:69]
	s_setprio 0
	s_barrier
	s_add_i32 s18, s47, s26
	v_lshl_add_u64 v[208:209], v[208:209], 0, s[0:1]
	s_mov_b32 m0, s18
	ds_read_b128 v[154:157], v247 offset:49152
	ds_read_b128 v[162:165], v247 offset:50176
	ds_read_b128 v[170:173], v247 offset:51200
	ds_read_b128 v[174:177], v247 offset:52224
	ds_read_b128 v[178:181], v247 offset:53248
	ds_read_b128 v[182:185], v247 offset:54272
	ds_read_b128 v[186:189], v247 offset:55296
	ds_read_b128 v[190:193], v247 offset:56320
	global_load_lds_dwordx4 v[208:209], off
	s_add_i32 m0, s18, 0x2000
	s_add_u32 s18, s22, 0xb0080
	v_lshl_add_u64 v[208:209], v[210:211], 0, s[0:1]
	s_addc_u32 s19, s23, 0
	s_add_i32 s22, s48, s26
	global_load_lds_dwordx4 v[208:209], off
	v_lshl_add_u64 v[208:209], s[18:19], 0, v[198:199]
	s_mov_b32 m0, s22
	s_nop 0
	global_load_lds_dwordx4 v[208:209], off
	v_lshl_add_u64 v[208:209], s[18:19], 0, v[196:197]
	s_add_i32 m0, s22, 0x2000
	s_nop 0
	global_load_lds_dwordx4 v[208:209], off
	v_lshl_add_u64 v[208:209], v[212:213], 0, s[0:1]
	s_mov_b32 m0, s34
	s_nop 0
	global_load_lds_dwordx4 v[208:209], off
	v_lshl_add_u64 v[208:209], v[214:215], 0, s[0:1]
	s_mov_b32 m0, s35
	s_nop 0
	global_load_lds_dwordx4 v[208:209], off
	s_waitcnt vmcnt(8)
	s_waitcnt lgkmcnt(0)
	s_barrier
	s_setprio 1
	v_mfma_f32_16x16x32_bf16 v[62:65], v[90:93], v[154:157], v[62:65]
	v_mfma_f32_16x16x32_bf16 v[58:61], v[114:117], v[154:157], v[58:61]
	v_mfma_f32_16x16x32_bf16 v[46:49], v[90:93], v[170:173], v[46:49]
	v_mfma_f32_16x16x32_bf16 v[42:45], v[114:117], v[170:173], v[42:45]
	v_mfma_f32_16x16x32_bf16 v[30:33], v[90:93], v[178:181], v[30:33]
	v_mfma_f32_16x16x32_bf16 v[26:29], v[114:117], v[178:181], v[26:29]
	v_mfma_f32_16x16x32_bf16 v[14:17], v[90:93], v[186:189], v[14:17]
	v_mfma_f32_16x16x32_bf16 v[10:13], v[114:117], v[186:189], v[10:13]
	v_mfma_f32_16x16x32_bf16 v[62:65], v[102:105], v[162:165], v[62:65]
	v_mfma_f32_16x16x32_bf16 v[58:61], v[122:125], v[162:165], v[58:61]
	v_mfma_f32_16x16x32_bf16 v[46:49], v[102:105], v[174:177], v[46:49]
	v_mfma_f32_16x16x32_bf16 v[42:45], v[122:125], v[174:177], v[42:45]
	v_mfma_f32_16x16x32_bf16 v[30:33], v[102:105], v[182:185], v[30:33]
	v_mfma_f32_16x16x32_bf16 v[26:29], v[122:125], v[182:185], v[26:29]
	v_mfma_f32_16x16x32_bf16 v[14:17], v[102:105], v[190:193], v[14:17]
	v_mfma_f32_16x16x32_bf16 v[10:13], v[122:125], v[190:193], v[10:13]
	v_mfma_f32_16x16x32_bf16 v[54:57], v[130:133], v[154:157], v[54:57]
	v_mfma_f32_16x16x32_bf16 v[50:53], v[146:149], v[154:157], v[50:53]
	v_mfma_f32_16x16x32_bf16 v[38:41], v[130:133], v[170:173], v[38:41]
	v_mfma_f32_16x16x32_bf16 v[34:37], v[146:149], v[170:173], v[34:37]
	v_mfma_f32_16x16x32_bf16 v[22:25], v[130:133], v[178:181], v[22:25]
	v_mfma_f32_16x16x32_bf16 v[18:21], v[146:149], v[178:181], v[18:21]
	v_mfma_f32_16x16x32_bf16 v[6:9], v[130:133], v[186:189], v[6:9]
	v_mfma_f32_16x16x32_bf16 v[2:5], v[146:149], v[186:189], v[2:5]
	v_mfma_f32_16x16x32_bf16 v[54:57], v[142:145], v[162:165], v[54:57]
	v_mfma_f32_16x16x32_bf16 v[50:53], v[150:153], v[162:165], v[50:53]
	v_mfma_f32_16x16x32_bf16 v[38:41], v[142:145], v[174:177], v[38:41]
	v_mfma_f32_16x16x32_bf16 v[34:37], v[150:153], v[174:177], v[34:37]
	v_mfma_f32_16x16x32_bf16 v[22:25], v[142:145], v[182:185], v[22:25]
	v_mfma_f32_16x16x32_bf16 v[18:21], v[150:153], v[182:185], v[18:21]
	v_mfma_f32_16x16x32_bf16 v[6:9], v[142:145], v[190:193], v[6:9]
	v_mfma_f32_16x16x32_bf16 v[2:5], v[150:153], v[190:193], v[2:5]
	s_setprio 0
	s_barrier
	s_add_i32 s46, s46, 2
	s_add_u32 s44, s44, 0x100
	s_addc_u32 s45, s45, 0
	s_cmp_gt_u32 s46, 41
	s_mov_b64 s[18:19], s[20:21]
	s_cbranch_scc0 .LBB0_636
	s_and_b64 vcc, exec, s[10:11]
	s_cbranch_vccz .LBB0_639
	s_barrier

.LBB0_688:
	s_add_u32 s20, s44, s18
	s_addc_u32 s21, s45, s19
	s_add_u32 s20, s20, 0x5000100
	s_addc_u32 s21, s21, 0
	s_add_u32 s49, s46, s18
	s_addc_u32 s50, s47, s19
	s_add_i32 s51, 0, 0x10000
	s_cmpk_eq_i32 s18, 0x700
	s_cselect_b32 s23, s39, s21
	s_cselect_b32 s22, s17, s20
	v_add_u32_e32 v144, s51, v148
	s_cselect_b32 s21, s43, s50
	s_cselect_b32 s20, s42, s49
	s_add_i32 s49, 0, 0x14000
	ds_read_b128 v[140:143], v144
	ds_read_b128 v[154:157], v144 offset:1024
	ds_read_b128 v[158:161], v144 offset:2048
	ds_read_b128 v[162:165], v144 offset:3072
	v_add_u32_e32 v144, s49, v148
	ds_read_b128 v[166:169], v144
	ds_read_b128 v[170:173], v144 offset:1024
	ds_read_b128 v[174:177], v144 offset:2048
	ds_read_b128 v[178:181], v144 offset:3072
	v_lshl_add_u64 v[144:145], v[136:137], 0, s[18:19]
	s_add_i32 m0, s24, 0xc000
	ds_read_b128 v[182:185], v152
	ds_read_b128 v[186:189], v152 offset:1024
	ds_read_b128 v[190:193], v152 offset:2048
	ds_read_b128 v[196:199], v152 offset:3072
	ds_read_b128 v[202:205], v152 offset:4096
	ds_read_b128 v[206:209], v152 offset:5120
	ds_read_b128 v[210:213], v152 offset:6144
	ds_read_b128 v[214:217], v152 offset:7168
	global_load_lds_dwordx4 v[144:145], off
	v_lshl_add_u64 v[144:145], v[138:139], 0, s[18:19]
	s_add_i32 m0, s24, 0xe000
	s_nop 0
	global_load_lds_dwordx4 v[144:145], off
	s_waitcnt vmcnt(8)
	s_waitcnt lgkmcnt(0)
	s_barrier
	s_setprio 1
	v_mfma_f32_16x16x32_bf16 v[126:129], v[140:143], v[182:185], v[126:129]
	v_mfma_f32_16x16x32_bf16 v[122:125], v[158:161], v[182:185], v[122:125]
	v_mfma_f32_16x16x32_bf16 v[110:113], v[140:143], v[190:193], v[110:113]
	v_mfma_f32_16x16x32_bf16 v[106:109], v[158:161], v[190:193], v[106:109]
	v_mfma_f32_16x16x32_bf16 v[94:97], v[140:143], v[202:205], v[94:97]
	v_mfma_f32_16x16x32_bf16 v[90:93], v[158:161], v[202:205], v[90:93]
	v_mfma_f32_16x16x32_bf16 v[78:81], v[140:143], v[210:213], v[78:81]
	v_mfma_f32_16x16x32_bf16 v[74:77], v[158:161], v[210:213], v[74:77]
	v_mfma_f32_16x16x32_bf16 v[126:129], v[154:157], v[186:189], v[126:129]
	v_mfma_f32_16x16x32_bf16 v[122:125], v[162:165], v[186:189], v[122:125]
	v_mfma_f32_16x16x32_bf16 v[110:113], v[154:157], v[196:199], v[110:113]
	v_mfma_f32_16x16x32_bf16 v[106:109], v[162:165], v[196:199], v[106:109]
	v_mfma_f32_16x16x32_bf16 v[94:97], v[154:157], v[206:209], v[94:97]
	v_mfma_f32_16x16x32_bf16 v[90:93], v[162:165], v[206:209], v[90:93]
	v_mfma_f32_16x16x32_bf16 v[78:81], v[154:157], v[214:217], v[78:81]
	v_mfma_f32_16x16x32_bf16 v[74:77], v[162:165], v[214:217], v[74:77]
	v_mfma_f32_16x16x32_bf16 v[118:121], v[166:169], v[182:185], v[118:121]
	v_mfma_f32_16x16x32_bf16 v[114:117], v[174:177], v[182:185], v[114:117]
	v_mfma_f32_16x16x32_bf16 v[102:105], v[166:169], v[190:193], v[102:105]
	v_mfma_f32_16x16x32_bf16 v[98:101], v[174:177], v[190:193], v[98:101]
	v_mfma_f32_16x16x32_bf16 v[86:89], v[166:169], v[202:205], v[86:89]
	v_mfma_f32_16x16x32_bf16 v[82:85], v[174:177], v[202:205], v[82:85]
	v_mfma_f32_16x16x32_bf16 v[70:73], v[166:169], v[210:213], v[70:73]
	v_mfma_f32_16x16x32_bf16 v[66:69], v[174:177], v[210:213], v[66:69]
	v_mfma_f32_16x16x32_bf16 v[118:121], v[170:173], v[186:189], v[118:121]
	v_mfma_f32_16x16x32_bf16 v[114:117], v[178:181], v[186:189], v[114:117]
	v_mfma_f32_16x16x32_bf16 v[102:105], v[170:173], v[196:199], v[102:105]
	v_mfma_f32_16x16x32_bf16 v[98:101], v[178:181], v[196:199], v[98:101]
	v_mfma_f32_16x16x32_bf16 v[86:89], v[170:173], v[206:209], v[86:89]
	v_mfma_f32_16x16x32_bf16 v[82:85], v[178:181], v[206:209], v[82:85]
	v_mfma_f32_16x16x32_bf16 v[70:73], v[170:173], v[214:217], v[70:73]
	v_mfma_f32_16x16x32_bf16 v[66:69], v[178:181], v[214:217], v[66:69]
	s_setprio 0
	s_barrier
	s_cmp_eq_u32 s99, 0
	s_cbranch_scc1 .Lbgc_it_skip
	s_mov_b64 exec, s[100:101]
	s_nop 0
	global_store_dwordx4 v[230:231], v[232:235], off nt
	s_mov_b64 exec, -1
	v_add_u32_e32 v226, 64, v226
	v_add_u32_e32 v227, 1, v227
	v_cmp_le_i32_e32 vcc, 0x1ffc0, v226
	v_subrev_u32_e32 v236, 0x1ffc0, v226
	s_nop 0
	v_cndmask_b32_e32 v226, v226, v236, vcc
	v_cndmask_b32_e64 v238, 0, 1, vcc
	v_add_u32_e32 v227, v227, v238
	v_mov_b32_e32 v236, 0x200400
	v_mov_b32_e32 v238, 0x200800
	v_cndmask_b32_e32 v236, v236, v238, vcc
	v_lshl_add_u64 v[228:229], v[228:229], 0, v[236:237]
	v_lshl_add_u64 v[230:231], v[230:231], 0, v[236:237]
	v_cmp_gt_i32_e32 vcc, 64, v227
	s_nop 1
	s_mov_b64 s[100:101], vcc
	s_mov_b64 exec, vcc
	s_nop 0
	global_load_dwordx4 v[232:235], v[228:229], off nt
	s_mov_b64 exec, -1
	s_cmp_lg_u64 s[100:101], 0
	s_cselect_b32 s99, 1, 0
.Lbgc_it_skip:
	s_add_i32 s50, s51, s2
	v_lshl_add_u64 v[144:145], s[20:21], 0, v[0:1]
	s_mov_b32 m0, s50
	ds_read_b128 v[182:185], v152 offset:16384
	ds_read_b128 v[186:189], v152 offset:17408
	ds_read_b128 v[190:193], v152 offset:18432
	ds_read_b128 v[196:199], v152 offset:19456
	ds_read_b128 v[202:205], v152 offset:20480
	ds_read_b128 v[206:209], v152 offset:21504
	ds_read_b128 v[210:213], v152 offset:22528
	ds_read_b128 v[214:217], v152 offset:23552
	global_load_lds_dwordx4 v[144:145], off
	s_add_i32 m0, s50, 0x2000
	s_add_u32 s50, s20, 0x40000
	v_lshl_add_u64 v[218:219], s[20:21], 0, v[130:131]
	s_addc_u32 s51, s21, 0
	s_add_i32 s49, s49, s2
	global_load_lds_dwordx4 v[218:219], off
	v_lshl_add_u64 v[220:221], s[50:51], 0, v[0:1]
	s_mov_b32 m0, s49
	v_lshl_add_u64 v[222:223], s[22:23], 0, v[130:131]
	global_load_lds_dwordx4 v[220:221], off
	v_lshl_add_u64 v[220:221], s[50:51], 0, v[130:131]
	s_add_i32 m0, s49, 0x2000
	s_nop 0
	global_load_lds_dwordx4 v[220:221], off
	v_lshl_add_u64 v[220:221], s[22:23], 0, v[0:1]
	s_mov_b32 m0, s24
	s_nop 0
	global_load_lds_dwordx4 v[220:221], off
	s_mov_b32 m0, s25
	s_nop 0
	global_load_lds_dwordx4 v[222:223], off
	s_waitcnt vmcnt(8)
	s_waitcnt lgkmcnt(0)
	s_barrier
	s_setprio 1
	v_mfma_f32_16x16x32_bf16 v[62:65], v[140:143], v[182:185], v[62:65]
	v_mfma_f32_16x16x32_bf16 v[58:61], v[158:161], v[182:185], v[58:61]
	v_mfma_f32_16x16x32_bf16 v[46:49], v[140:143], v[190:193], v[46:49]
	v_mfma_f32_16x16x32_bf16 v[42:45], v[158:161], v[190:193], v[42:45]
	v_mfma_f32_16x16x32_bf16 v[30:33], v[140:143], v[202:205], v[30:33]
	v_mfma_f32_16x16x32_bf16 v[26:29], v[158:161], v[202:205], v[26:29]
	v_mfma_f32_16x16x32_bf16 v[14:17], v[140:143], v[210:213], v[14:17]
	v_mfma_f32_16x16x32_bf16 v[10:13], v[158:161], v[210:213], v[10:13]
	v_mfma_f32_16x16x32_bf16 v[62:65], v[154:157], v[186:189], v[62:65]
	v_mfma_f32_16x16x32_bf16 v[58:61], v[162:165], v[186:189], v[58:61]
	v_mfma_f32_16x16x32_bf16 v[46:49], v[154:157], v[196:199], v[46:49]
	v_mfma_f32_16x16x32_bf16 v[42:45], v[162:165], v[196:199], v[42:45]
	v_mfma_f32_16x16x32_bf16 v[30:33], v[154:157], v[206:209], v[30:33]
	v_mfma_f32_16x16x32_bf16 v[26:29], v[162:165], v[206:209], v[26:29]
	v_mfma_f32_16x16x32_bf16 v[14:17], v[154:157], v[214:217], v[14:17]
	v_mfma_f32_16x16x32_bf16 v[10:13], v[162:165], v[214:217], v[10:13]
	v_mfma_f32_16x16x32_bf16 v[54:57], v[166:169], v[182:185], v[54:57]
	v_mfma_f32_16x16x32_bf16 v[50:53], v[174:177], v[182:185], v[50:53]
	v_mfma_f32_16x16x32_bf16 v[38:41], v[166:169], v[190:193], v[38:41]
	v_mfma_f32_16x16x32_bf16 v[34:37], v[174:177], v[190:193], v[34:37]
	v_mfma_f32_16x16x32_bf16 v[22:25], v[166:169], v[202:205], v[22:25]
	v_mfma_f32_16x16x32_bf16 v[18:21], v[174:177], v[202:205], v[18:21]
	v_mfma_f32_16x16x32_bf16 v[6:9], v[166:169], v[210:213], v[6:9]
	v_mfma_f32_16x16x32_bf16 v[2:5], v[174:177], v[210:213], v[2:5]
	v_mfma_f32_16x16x32_bf16 v[54:57], v[170:173], v[186:189], v[54:57]
	v_mfma_f32_16x16x32_bf16 v[50:53], v[178:181], v[186:189], v[50:53]
	v_mfma_f32_16x16x32_bf16 v[38:41], v[170:173], v[196:199], v[38:41]
	v_mfma_f32_16x16x32_bf16 v[34:37], v[178:181], v[196:199], v[34:37]
	v_mfma_f32_16x16x32_bf16 v[22:25], v[170:173], v[206:209], v[22:25]
	v_mfma_f32_16x16x32_bf16 v[18:21], v[178:181], v[206:209], v[18:21]
	v_mfma_f32_16x16x32_bf16 v[6:9], v[170:173], v[214:217], v[6:9]
	v_mfma_f32_16x16x32_bf16 v[2:5], v[178:181], v[214:217], v[2:5]
	s_setprio 0
	s_barrier
	s_add_i32 s49, 0, 0x18000
	v_add_u32_e32 v153, s49, v148
	s_add_i32 s50, 0, 0x1c000
	ds_read_b128 v[140:143], v153
	ds_read_b128 v[154:157], v153 offset:1024
	ds_read_b128 v[158:161], v153 offset:2048
	ds_read_b128 v[162:165], v153 offset:3072
	v_add_u32_e32 v153, s50, v148
	ds_read_b128 v[166:169], v153
	ds_read_b128 v[170:173], v153 offset:1024
	ds_read_b128 v[174:177], v153 offset:2048
	ds_read_b128 v[178:181], v153 offset:3072
	s_add_u32 s22, s22, 0x40000
	s_addc_u32 s23, s23, 0
	s_mov_b32 m0, s26
	v_lshl_add_u64 v[224:225], s[22:23], 0, v[0:1]
	ds_read_b128 v[182:185], v152 offset:32768
	ds_read_b128 v[186:189], v152 offset:33792
	ds_read_b128 v[190:193], v152 offset:34816
	ds_read_b128 v[196:199], v152 offset:35840
	ds_read_b128 v[202:205], v152 offset:36864
	ds_read_b128 v[206:209], v152 offset:37888
	ds_read_b128 v[210:213], v152 offset:38912
	ds_read_b128 v[214:217], v152 offset:39936
	global_load_lds_dwordx4 v[224:225], off
	v_lshl_add_u64 v[224:225], s[22:23], 0, v[130:131]
	s_mov_b32 m0, s27
	s_nop 0
	global_load_lds_dwordx4 v[224:225], off
	s_waitcnt vmcnt(8)
	s_waitcnt lgkmcnt(0)
	s_barrier
	s_setprio 1
	v_mfma_f32_16x16x32_bf16 v[126:129], v[140:143], v[182:185], v[126:129]
	v_mfma_f32_16x16x32_bf16 v[122:125], v[158:161], v[182:185], v[122:125]
	v_mfma_f32_16x16x32_bf16 v[110:113], v[140:143], v[190:193], v[110:113]
	v_mfma_f32_16x16x32_bf16 v[106:109], v[158:161], v[190:193], v[106:109]
	v_mfma_f32_16x16x32_bf16 v[94:97], v[140:143], v[202:205], v[94:97]
	v_mfma_f32_16x16x32_bf16 v[90:93], v[158:161], v[202:205], v[90:93]
	v_mfma_f32_16x16x32_bf16 v[78:81], v[140:143], v[210:213], v[78:81]
	v_mfma_f32_16x16x32_bf16 v[74:77], v[158:161], v[210:213], v[74:77]
	v_mfma_f32_16x16x32_bf16 v[126:129], v[154:157], v[186:189], v[126:129]
	v_mfma_f32_16x16x32_bf16 v[122:125], v[162:165], v[186:189], v[122:125]
	v_mfma_f32_16x16x32_bf16 v[110:113], v[154:157], v[196:199], v[110:113]
	v_mfma_f32_16x16x32_bf16 v[106:109], v[162:165], v[196:199], v[106:109]
	v_mfma_f32_16x16x32_bf16 v[94:97], v[154:157], v[206:209], v[94:97]
	v_mfma_f32_16x16x32_bf16 v[90:93], v[162:165], v[206:209], v[90:93]
	v_mfma_f32_16x16x32_bf16 v[78:81], v[154:157], v[214:217], v[78:81]
	v_mfma_f32_16x16x32_bf16 v[74:77], v[162:165], v[214:217], v[74:77]
	v_mfma_f32_16x16x32_bf16 v[118:121], v[166:169], v[182:185], v[118:121]
	v_mfma_f32_16x16x32_bf16 v[114:117], v[174:177], v[182:185], v[114:117]
	v_mfma_f32_16x16x32_bf16 v[102:105], v[166:169], v[190:193], v[102:105]
	v_mfma_f32_16x16x32_bf16 v[98:101], v[174:177], v[190:193], v[98:101]
	v_mfma_f32_16x16x32_bf16 v[86:89], v[166:169], v[202:205], v[86:89]
	v_mfma_f32_16x16x32_bf16 v[82:85], v[174:177], v[202:205], v[82:85]
	v_mfma_f32_16x16x32_bf16 v[70:73], v[166:169], v[210:213], v[70:73]
	v_mfma_f32_16x16x32_bf16 v[66:69], v[174:177], v[210:213], v[66:69]
	v_mfma_f32_16x16x32_bf16 v[118:121], v[170:173], v[186:189], v[118:121]
	v_mfma_f32_16x16x32_bf16 v[114:117], v[178:181], v[186:189], v[114:117]
	v_mfma_f32_16x16x32_bf16 v[102:105], v[170:173], v[196:199], v[102:105]
	v_mfma_f32_16x16x32_bf16 v[98:101], v[178:181], v[196:199], v[98:101]
	v_mfma_f32_16x16x32_bf16 v[86:89], v[170:173], v[206:209], v[86:89]
	v_mfma_f32_16x16x32_bf16 v[82:85], v[178:181], v[206:209], v[82:85]
	v_mfma_f32_16x16x32_bf16 v[70:73], v[170:173], v[214:217], v[70:73]
	v_mfma_f32_16x16x32_bf16 v[66:69], v[178:181], v[214:217], v[66:69]
	s_setprio 0
	s_barrier
	s_add_i32 s22, s49, s2
	v_lshl_add_u64 v[144:145], v[144:145], 0, s[0:1]
	s_mov_b32 m0, s22
	ds_read_b128 v[182:185], v152 offset:49152
	ds_read_b128 v[186:189], v152 offset:50176
	ds_read_b128 v[190:193], v152 offset:51200
	ds_read_b128 v[196:199], v152 offset:52224
	ds_read_b128 v[202:205], v152 offset:53248
	ds_read_b128 v[206:209], v152 offset:54272
	ds_read_b128 v[210:213], v152 offset:55296
	ds_read_b128 v[214:217], v152 offset:56320
	global_load_lds_dwordx4 v[144:145], off
	s_add_i32 m0, s22, 0x2000
	s_add_u32 s20, s20, 0x40080
	v_lshl_add_u64 v[144:145], v[218:219], 0, s[0:1]
	s_addc_u32 s21, s21, 0
	s_add_i32 s22, s50, s2
	global_load_lds_dwordx4 v[144:145], off
	v_lshl_add_u64 v[144:145], s[20:21], 0, v[0:1]
	s_mov_b32 m0, s22
	s_nop 0
	global_load_lds_dwordx4 v[144:145], off
	v_lshl_add_u64 v[144:145], s[20:21], 0, v[130:131]
	s_add_i32 m0, s22, 0x2000
	s_nop 0
	global_load_lds_dwordx4 v[144:145], off
	v_lshl_add_u64 v[144:145], v[220:221], 0, s[0:1]
	s_mov_b32 m0, s28
	s_nop 0
	global_load_lds_dwordx4 v[144:145], off
	v_lshl_add_u64 v[144:145], v[222:223], 0, s[0:1]
	s_mov_b32 m0, s29
	s_nop 0
	global_load_lds_dwordx4 v[144:145], off
	s_waitcnt vmcnt(8)
	s_waitcnt lgkmcnt(0)
	s_barrier
	s_setprio 1
	v_mfma_f32_16x16x32_bf16 v[62:65], v[140:143], v[182:185], v[62:65]
	v_mfma_f32_16x16x32_bf16 v[58:61], v[158:161], v[182:185], v[58:61]
	v_mfma_f32_16x16x32_bf16 v[46:49], v[140:143], v[190:193], v[46:49]
	v_mfma_f32_16x16x32_bf16 v[42:45], v[158:161], v[190:193], v[42:45]
	v_mfma_f32_16x16x32_bf16 v[30:33], v[140:143], v[202:205], v[30:33]
	v_mfma_f32_16x16x32_bf16 v[26:29], v[158:161], v[202:205], v[26:29]
	v_mfma_f32_16x16x32_bf16 v[14:17], v[140:143], v[210:213], v[14:17]
	v_mfma_f32_16x16x32_bf16 v[10:13], v[158:161], v[210:213], v[10:13]
	v_mfma_f32_16x16x32_bf16 v[62:65], v[154:157], v[186:189], v[62:65]
	v_mfma_f32_16x16x32_bf16 v[58:61], v[162:165], v[186:189], v[58:61]
	v_mfma_f32_16x16x32_bf16 v[46:49], v[154:157], v[196:199], v[46:49]
	v_mfma_f32_16x16x32_bf16 v[42:45], v[162:165], v[196:199], v[42:45]
	v_mfma_f32_16x16x32_bf16 v[30:33], v[154:157], v[206:209], v[30:33]
	v_mfma_f32_16x16x32_bf16 v[26:29], v[162:165], v[206:209], v[26:29]
	v_mfma_f32_16x16x32_bf16 v[14:17], v[154:157], v[214:217], v[14:17]
	v_mfma_f32_16x16x32_bf16 v[10:13], v[162:165], v[214:217], v[10:13]
	v_mfma_f32_16x16x32_bf16 v[54:57], v[166:169], v[182:185], v[54:57]
	v_mfma_f32_16x16x32_bf16 v[50:53], v[174:177], v[182:185], v[50:53]
	v_mfma_f32_16x16x32_bf16 v[38:41], v[166:169], v[190:193], v[38:41]
	v_mfma_f32_16x16x32_bf16 v[34:37], v[174:177], v[190:193], v[34:37]
	v_mfma_f32_16x16x32_bf16 v[22:25], v[166:169], v[202:205], v[22:25]
	v_mfma_f32_16x16x32_bf16 v[18:21], v[174:177], v[202:205], v[18:21]
	v_mfma_f32_16x16x32_bf16 v[6:9], v[166:169], v[210:213], v[6:9]
	v_mfma_f32_16x16x32_bf16 v[2:5], v[174:177], v[210:213], v[2:5]
	v_mfma_f32_16x16x32_bf16 v[54:57], v[170:173], v[186:189], v[54:57]
	v_mfma_f32_16x16x32_bf16 v[50:53], v[178:181], v[186:189], v[50:53]
	v_mfma_f32_16x16x32_bf16 v[38:41], v[170:173], v[196:199], v[38:41]
	v_mfma_f32_16x16x32_bf16 v[34:37], v[178:181], v[196:199], v[34:37]
	v_mfma_f32_16x16x32_bf16 v[22:25], v[170:173], v[206:209], v[22:25]
	v_mfma_f32_16x16x32_bf16 v[18:21], v[178:181], v[206:209], v[18:21]
	v_mfma_f32_16x16x32_bf16 v[6:9], v[170:173], v[214:217], v[6:9]
	v_mfma_f32_16x16x32_bf16 v[2:5], v[178:181], v[214:217], v[2:5]
	s_setprio 0
	s_barrier
	s_add_i32 s48, s48, 2
	s_add_u32 s18, s18, 0x100
	s_addc_u32 s19, s19, 0
	s_cmp_gt_u32 s48, 13
	s_cbranch_scc0 .LBB0_688
	s_and_b64 vcc, exec, s[8:9]
	s_cbranch_vccz .LBB0_691
	s_barrier
